# v27: + S5 passes: per-item U staging loop hand-unrolled, all ss/X/gain loads issued together (was 4 dependent round trips before every scan)
# baseline (speedup 1.0000x reference)
.LBB0_285:
	v_lshl_add_u32 v16, s56, 3, v117
	v_mul_hi_i32 v17, v16, s4
	v_lshrrev_b32_e32 v18, 31, v17
	v_ashrrev_i32_e32 v17, 8, v17
	v_add_u32_e32 v17, v17, v18
	v_mul_i32_i24_e32 v18, 0x5fa, v17
	v_and_b32_e32 v19, 31, v17
	v_sub_u32_e32 v18, v16, v18
	v_cmp_gt_u32_e64 s[8:9], 32, v17
	v_mul_u32_u24_e32 v19, 0x300000, v19
	v_lshlrev_b32_e32 v88, 2, v19
	v_cndmask_b32_e64 v17, v120, v121, s[8:9]
	v_cndmask_b32_e64 v16, v122, v123, s[8:9]
	v_mov_b32_e32 v89, v81
	v_lshlrev_b32_e32 v90, 9, v18
	v_lshl_add_u64 v[16:17], v[16:17], 0, v[88:89]
	v_ashrrev_i32_e32 v91, 31, v90
	v_lshl_add_u64 v[16:17], v[90:91], 4, v[16:17]
	v_lshl_add_u64 v[16:17], v[16:17], 0, v[84:85]
	v_add_co_u32_e32 v20, vcc, s5, v16
	v_lshl_add_u64 v[18:19], v[16:17], 0, s[12:13]
	s_nop 0
	v_addc_co_u32_e32 v21, vcc, 0, v17, vcc
	v_add_co_u32_e32 v16, vcc, 0xd000, v16
	v_addc_co_u32_e32 v17, vcc, 0, v17, vcc
	s_ashr_i32 s30, s56, 10
	s_bfe_u32 s62, s56, 0x70003
	s_and_b32 s31, s56, 7
	s_and_saveexec_b64 s[34:35], s[6:7]
	s_cbranch_execz .LBB0_288
	s_lshl_b32 s36, s30, 13
	s_lshl_b32 s37, s62, 6
	s_or_b32 s63, s37, s36
	s_lshl_b32 s52, s31, 9
	s_add_u32 s36, s38, s52
	s_addc_u32 s37, s39, 0
	s_add_u32 s52, s42, s52
	s_addc_u32 s53, s43, 0
	s_mov_b64 s[54:55], 0
	v_and_b32_e32 v80, 31, v116
	v_lshlrev_b32_e32 v80, 4, v80
	v_lshrrev_b32_e32 v29, 5, v116
	v_add_u32_e32 v16, s63, v29
	v_lshlrev_b32_e32 v29, 9, v29
	v_add_u32_e32 v29, v29, v80
	v_lshlrev_b32_e32 v255, 2, v16
	global_load_dword v127, v255, s[22:23]
	v_lshl_add_u32 v17, v16, 12, v80
	global_load_dwordx4 v[18:21], v17, s[36:37]
	global_load_dwordx4 v[22:25], v80, s[52:53]
	global_load_dword v30, v255, s[22:23] offset:64
	v_add_u32_e32 v16, 0x10000, v17
	global_load_dwordx4 v[242:245], v16, s[36:37]
	global_load_dword v31, v255, s[22:23] offset:128
	v_add_u32_e32 v16, 0x20000, v17
	global_load_dwordx4 v[246:249], v16, s[36:37]
	global_load_dword v254, v255, s[22:23] offset:192
	v_add_u32_e32 v16, 0x30000, v17
	global_load_dwordx4 v[250:253], v16, s[36:37]
	s_waitcnt vmcnt(0)
	v_fmamk_f32 v26, v30, 0x3a800000, v124
	v_mul_f32_e32 v28, 0x4b800000, v26
	v_cmp_gt_f32_e64 vcc, s46, v26
	s_nop 1
	v_cndmask_b32_e64 v26, v26, v28, vcc
	v_rsq_f32_e32 v26, v26
	s_nop 0
	v_mul_f32_e32 v28, 0x45800000, v26
	v_cndmask_b32_e64 v26, v26, v28, vcc
	v_pk_mul_f32 v[242:243], v[242:243], v[26:27] op_sel_hi:[1,0]
	v_pk_mul_f32 v[244:245], v[244:245], v[26:27] op_sel_hi:[1,0]
	v_pk_mul_f32 v[242:243], v[22:23], v[242:243]
	v_pk_mul_f32 v[244:245], v[24:25], v[244:245]
	ds_write_b128 v29, v[242:245] offset:8192
	v_fmamk_f32 v26, v31, 0x3a800000, v124
	v_mul_f32_e32 v28, 0x4b800000, v26
	v_cmp_gt_f32_e64 vcc, s46, v26
	s_nop 1
	v_cndmask_b32_e64 v26, v26, v28, vcc
	v_rsq_f32_e32 v26, v26
	s_nop 0
	v_mul_f32_e32 v28, 0x45800000, v26
	v_cndmask_b32_e64 v26, v26, v28, vcc
	v_pk_mul_f32 v[246:247], v[246:247], v[26:27] op_sel_hi:[1,0]
	v_pk_mul_f32 v[248:249], v[248:249], v[26:27] op_sel_hi:[1,0]
	v_pk_mul_f32 v[246:247], v[22:23], v[246:247]
	v_pk_mul_f32 v[248:249], v[24:25], v[248:249]
	ds_write_b128 v29, v[246:249] offset:16384
	v_fmamk_f32 v26, v254, 0x3a800000, v124
	v_mul_f32_e32 v28, 0x4b800000, v26
	v_cmp_gt_f32_e64 vcc, s46, v26
	s_nop 1
	v_cndmask_b32_e64 v26, v26, v28, vcc
	v_rsq_f32_e32 v26, v26
	s_nop 0
	v_mul_f32_e32 v28, 0x45800000, v26
	v_cndmask_b32_e64 v26, v26, v28, vcc
	v_pk_mul_f32 v[250:251], v[250:251], v[26:27] op_sel_hi:[1,0]
	v_pk_mul_f32 v[252:253], v[252:253], v[26:27] op_sel_hi:[1,0]
	v_pk_mul_f32 v[250:251], v[22:23], v[250:251]
	v_pk_mul_f32 v[252:253], v[24:25], v[252:253]
	ds_write_b128 v29, v[250:253] offset:24576
	v_fmamk_f32 v26, v127, 0x3a800000, v124
	v_mul_f32_e32 v28, 0x4b800000, v26
	v_cmp_gt_f32_e64 vcc, s46, v26
	s_nop 1
	v_cndmask_b32_e64 v26, v26, v28, vcc
	v_rsq_f32_e32 v26, v26
	s_nop 0
	v_mul_f32_e32 v28, 0x45800000, v26
	v_cndmask_b32_e64 v26, v26, v28, vcc
	v_pk_mul_f32 v[18:19], v[18:19], v[26:27] op_sel_hi:[1,0]
	v_pk_mul_f32 v[20:21], v[20:21], v[26:27] op_sel_hi:[1,0]
	v_pk_mul_f32 v[18:19], v[22:23], v[18:19]
	v_pk_mul_f32 v[20:21], v[24:25], v[20:21]
	ds_write_b128 v29, v[18:21]

.LBB0_328:
	s_lshl_b32 s77, s67, 5
	s_and_b32 s21, s47, 7
	v_cmp_gt_i32_e32 vcc, s77, v69
	s_and_saveexec_b64 s[52:53], vcc
	s_cbranch_execz .LBB0_331
	s_lshl_b32 s8, s21, 9
	s_add_u32 s54, s38, s8
	s_addc_u32 s55, s39, 0
	s_add_u32 s56, s42, s8
	s_addc_u32 s57, s43, 0
	s_mov_b64 s[64:65], 0
	v_and_b32_e32 v70, 31, v69
	v_lshlrev_b32_e32 v70, 4, v70
	v_lshrrev_b32_e32 v85, 5, v69
	v_add_u32_e32 v64, s63, v85
	v_lshlrev_b32_e32 v85, 9, v85
	v_add_u32_e32 v85, v85, v70
	v_lshlrev_b32_e32 v207, 2, v64
	global_load_dword v204, v207, s[22:23]
	v_lshl_add_u32 v65, v64, 12, v70
	global_load_dwordx4 v[104:107], v65, s[54:55]
	global_load_dwordx4 v[108:111], v70, s[56:57]
	s_cmpk_gt_u32 s77, 0x200
	s_cbranch_scc0 .Lus69_one
	global_load_dword v205, v207, s[22:23] offset:64
	v_add_u32_e32 v64, 0x10000, v65
	global_load_dwordx4 v[192:195], v64, s[54:55]
	global_load_dword v206, v207, s[22:23] offset:128
	v_add_u32_e32 v64, 0x20000, v65
	global_load_dwordx4 v[196:199], v64, s[54:55]
	global_load_dword v208, v207, s[22:23] offset:192
	v_add_u32_e32 v64, 0x30000, v65
	global_load_dwordx4 v[200:203], v64, s[54:55]
	s_waitcnt vmcnt(0)
	v_fmamk_f32 v66, v205, 0x3a800000, v183
	v_mul_f32_e32 v77, 0x4b800000, v66
	v_cmp_gt_f32_e64 s[8:9], s46, v66
	s_nop 1
	v_cndmask_b32_e64 v66, v66, v77, s[8:9]
	v_rsq_f32_e32 v66, v66
	s_nop 0
	v_mul_f32_e32 v77, 0x45800000, v66
	v_cndmask_b32_e64 v66, v66, v77, s[8:9]
	v_pk_mul_f32 v[192:193], v[192:193], v[66:67] op_sel_hi:[1,0]
	v_pk_mul_f32 v[194:195], v[194:195], v[66:67] op_sel_hi:[1,0]
	v_pk_mul_f32 v[192:193], v[108:109], v[192:193]
	v_pk_mul_f32 v[194:195], v[110:111], v[194:195]
	ds_write_b128 v85, v[192:195] offset:8192
	v_fmamk_f32 v66, v206, 0x3a800000, v183
	v_mul_f32_e32 v77, 0x4b800000, v66
	v_cmp_gt_f32_e64 s[8:9], s46, v66
	s_nop 1
	v_cndmask_b32_e64 v66, v66, v77, s[8:9]
	v_rsq_f32_e32 v66, v66
	s_nop 0
	v_mul_f32_e32 v77, 0x45800000, v66
	v_cndmask_b32_e64 v66, v66, v77, s[8:9]
	v_pk_mul_f32 v[196:197], v[196:197], v[66:67] op_sel_hi:[1,0]
	v_pk_mul_f32 v[198:199], v[198:199], v[66:67] op_sel_hi:[1,0]
	v_pk_mul_f32 v[196:197], v[108:109], v[196:197]
	v_pk_mul_f32 v[198:199], v[110:111], v[198:199]
	ds_write_b128 v85, v[196:199] offset:16384
	v_fmamk_f32 v66, v208, 0x3a800000, v183
	v_mul_f32_e32 v77, 0x4b800000, v66
	v_cmp_gt_f32_e64 s[8:9], s46, v66
	s_nop 1
	v_cndmask_b32_e64 v66, v66, v77, s[8:9]
	v_rsq_f32_e32 v66, v66
	s_nop 0
	v_mul_f32_e32 v77, 0x45800000, v66
	v_cndmask_b32_e64 v66, v66, v77, s[8:9]
	v_pk_mul_f32 v[200:201], v[200:201], v[66:67] op_sel_hi:[1,0]
	v_pk_mul_f32 v[202:203], v[202:203], v[66:67] op_sel_hi:[1,0]
	v_pk_mul_f32 v[200:201], v[108:109], v[200:201]
	v_pk_mul_f32 v[202:203], v[110:111], v[202:203]
	ds_write_b128 v85, v[200:203] offset:24576
.Lus69_one:
	s_waitcnt vmcnt(0)
	v_fmamk_f32 v66, v204, 0x3a800000, v183
	v_mul_f32_e32 v77, 0x4b800000, v66
	v_cmp_gt_f32_e64 s[8:9], s46, v66
	s_nop 1
	v_cndmask_b32_e64 v66, v66, v77, s[8:9]
	v_rsq_f32_e32 v66, v66
	s_nop 0
	v_mul_f32_e32 v77, 0x45800000, v66
	v_cndmask_b32_e64 v66, v66, v77, s[8:9]
	v_pk_mul_f32 v[104:105], v[104:105], v[66:67] op_sel_hi:[1,0]
	v_pk_mul_f32 v[106:107], v[106:107], v[66:67] op_sel_hi:[1,0]
	v_pk_mul_f32 v[104:105], v[108:109], v[104:105]
	v_pk_mul_f32 v[106:107], v[110:111], v[106:107]
	ds_write_b128 v85, v[104:107]
